# E37: fox_bias: first strided load no longer waited on its own; all nine prefix loads in flight together (both FoX instantiations); on E35
# speedup vs baseline: 1.0043x; 1.0043x over previous
.LBB0_1338:
	s_lshl_b64 s[16:17], s[60:61], 10
	s_mov_b64 s[14:15], src_shared_base
	s_add_u32 s6, s59, s16
	s_addc_u32 s14, s50, s17
	s_lshl_b64 s[96:97], s[18:19], 1
	s_add_u32 s94, s6, s96
	s_getreg_b32 s6, hwreg(HW_REG_HW_ID, 0, 6)
	s_addc_u32 s95, s14, s97
	s_and_b32 s6, s6, 63
	s_lshl_b32 s6, s6, 2
	s_add_i32 s6, s6, 0
	s_add_i32 s6, s6, 0x23e00
	v_mov_b32_e32 v4, s6
	v_mov_b32_e32 v5, s15
	flat_load_dword v172, v[4:5] sc0 sc1
	s_waitcnt vmcnt(0)
	s_add_i32 s6, s12, -1
	s_cmpk_gt_i32 s13, 0x1ff
	s_mov_b64 s[18:19], -1
	s_cbranch_scc1 .LBB0_1403
	s_waitcnt lgkmcnt(0)
	v_readfirstlane_b32 s13, v172
	v_mov_b32_e32 v153, v3
	s_mov_b64 s[14:15], src_shared_base
	v_lshl_add_u32 v2, s13, 6, v217
	v_mov_b32_e32 v19, 0
	v_readfirstlane_b32 s13, v2
	s_ashr_i32 s13, s13, 1
	s_andn2_b32 s13, s13, 31
	v_or_b32_e32 v146, s13, v212
	v_min_i32_e32 v4, s6, v146
	v_ashrrev_i32_e32 v5, 31, v4
	v_lshlrev_b64 v[4:5], 10, v[4:5]
	v_lshl_add_u64 v[4:5], s[94:95], 0, v[4:5]
	v_lshl_add_u64 v[4:5], v[4:5], 0, v[152:153]
	global_load_dwordx4 v[114:117], v[4:5], off
	global_load_dwordx4 v[118:121], v[4:5], off offset:32
	global_load_dwordx4 v[122:125], v[4:5], off offset:64
	global_load_dwordx4 v[126:129], v[4:5], off offset:96
	v_ashrrev_i32_e32 v4, 31, v2
	v_lshrrev_b32_e32 v4, 29, v4
	v_add_u32_e32 v5, v2, v4
	v_ashrrev_i32_e32 v4, 3, v5
	v_and_b32_e32 v5, -8, v5
	v_sub_u32_e32 v8, v2, v5
	v_ashrrev_i32_e32 v5, 31, v4
	v_lshlrev_b32_e32 v148, 3, v8
	v_lshlrev_b64 v[6:7], 9, v[4:5]
	v_ashrrev_i32_e32 v149, 31, v148
	v_lshl_add_u64 v[6:7], v[6:7], 0, v[148:149]
	v_lshlrev_b64 v[6:7], 1, v[6:7]
	v_lshl_add_u64 v[10:11], s[64:65], 0, v[6:7]
	v_lshl_add_u64 v[6:7], s[66:67], 0, v[6:7]
	v_add_u32_e32 v5, 0x200, v2
	global_load_dwordx4 v[134:137], v[6:7], off
	v_ashrrev_i32_e32 v6, 31, v5
	v_lshrrev_b32_e32 v6, 29, v6
	v_add_u32_e32 v7, v5, v6
	v_ashrrev_i32_e32 v6, 3, v7
	v_and_b32_e32 v7, -8, v7
	v_sub_u32_e32 v5, v5, v7
	v_ashrrev_i32_e32 v7, 31, v6
	v_lshlrev_b32_e32 v156, 3, v5
	global_load_dwordx4 v[130:133], v[10:11], off
	v_lshlrev_b64 v[10:11], 9, v[6:7]
	v_ashrrev_i32_e32 v157, 31, v156
	v_lshl_add_u64 v[10:11], v[10:11], 0, v[156:157]
	v_lshlrev_b64 v[10:11], 1, v[10:11]
	v_lshl_add_u64 v[12:13], s[64:65], 0, v[10:11]
	v_lshl_add_u64 v[10:11], s[66:67], 0, v[10:11]
	global_load_dwordx4 v[138:141], v[12:13], off
	global_load_dwordx4 v[142:145], v[10:11], off
	s_getreg_b32 s14, hwreg(HW_REG_HW_ID, 0, 6)
	s_and_b32 s14, s14, 63
	s_lshl_b32 s14, s14, 2
	s_add_i32 s14, s14, 0
	s_add_i32 s14, s14, 0x23e00
	v_mov_b32_e32 v10, s14
	v_mov_b32_e32 v11, s15
	flat_load_dword v7, v[10:11] sc0 sc1
	s_waitcnt vmcnt(0)
	v_mov_b32_e32 v10, 0
	s_waitcnt lgkmcnt(0)
	v_readfirstlane_b32 s14, v7
	s_nop 1
	v_lshl_add_u32 v13, s14, 6, v217
	v_lshl_add_u32 v7, v13, 3, v13
	v_cmp_gt_i32_e32 vcc, s9, v7
	v_mov_b32_e32 v199, 0
	s_and_saveexec_b64 s[20:21], vcc
	s_cbranch_execz .LBB0_1341
	v_mov_b32_e32 v9, s93
	v_mov_b32_e32 v10, s79
	v_cmp_gt_i32_e64 s[18:19], s11, v7
	v_subrev_u32_e32 v12, s11, v7
	s_nop 0
	v_cndmask_b32_e64 v11, v9, v10, s[18:19]
	v_mov_b32_e32 v9, s92
	v_mov_b32_e32 v10, s78
	v_cndmask_b32_e64 v10, v9, v10, s[18:19]
	v_ashrrev_i32_e32 v9, 31, v7
	v_cndmask_b32_e64 v15, 0, v9, s[18:19]
	v_cndmask_b32_e64 v14, v12, v7, s[18:19]
	v_lshlrev_b64 v[14:15], 5, v[14:15]
	v_lshl_add_u64 v[10:11], v[10:11], 0, v[14:15]
	global_load_dword v199, v[10:11], off

.LBB0_1357:
	s_or_b64 exec, exec, s[38:39]
	s_waitcnt vmcnt(0)
	v_add_f32_e32 v10, 0, v199
	v_add_f32_e32 v27, v10, v19
	v_add_f32_e32 v26, v27, v21
	v_add_f32_e32 v25, v26, v20
	v_add_f32_e32 v24, v25, v23
	v_add_f32_e32 v22, v24, v22
	v_add_f32_e32 v21, v22, v29
	v_add_f32_e32 v20, v21, v28
	v_add_f32_e32 v19, v20, v30
	ds_bpermute_b32 v23, v179, v19
	v_readlane_b32 s14, v244, 26
	v_readlane_b32 s15, v244, 27
	v_ashrrev_i32_e32 v29, 6, v13
	s_waitcnt lgkmcnt(0)
	v_add_f32_e32 v23, v19, v23
	v_cndmask_b32_e64 v23, v23, v19, s[0:1]
	ds_bpermute_b32 v28, v180, v23
	s_waitcnt lgkmcnt(0)
	v_add_f32_e32 v28, v23, v28
	v_cndmask_b32_e64 v23, v28, v23, s[74:75]
	ds_bpermute_b32 v28, v181, v23
	s_waitcnt lgkmcnt(0)
	v_add_f32_e32 v28, v23, v28
	v_cndmask_b32_e64 v23, v28, v23, s[14:15]
	ds_bpermute_b32 v28, v182, v23
	v_readlane_b32 s14, v244, 28
	v_readlane_b32 s15, v244, 29
	s_waitcnt lgkmcnt(0)
	v_add_f32_e32 v28, v23, v28
	v_cndmask_b32_e64 v23, v28, v23, s[14:15]
	ds_bpermute_b32 v28, v183, v23
	v_readlane_b32 s14, v244, 30
	v_readlane_b32 s15, v244, 31
	s_waitcnt lgkmcnt(0)
	v_add_f32_e32 v28, v23, v28
	v_cndmask_b32_e64 v23, v28, v23, s[14:15]
	ds_bpermute_b32 v28, v184, v23
	s_waitcnt lgkmcnt(0)
	v_add_f32_e32 v28, v23, v28
	s_mov_b64 s[36:37], exec
	v_readlane_b32 s14, v244, 34
	v_readlane_b32 s15, v244, 35
	s_and_b64 s[14:15], s[36:37], s[14:15]
	s_mov_b64 exec, s[14:15]
	v_lshl_add_u32 v30, v29, 2, 0
	v_add_u32_e32 v30, 0x19800, v30
	ds_write_b32 v30, v28
	s_or_b64 exec, exec, s[36:37]
	v_readlane_b32 s14, v244, 32
	v_readlane_b32 s15, v244, 33
	v_cmp_lt_i32_e64 s[36:37], 0, v29
	s_waitcnt lgkmcnt(0)
	v_cndmask_b32_e64 v23, v28, v23, s[14:15]
	v_sub_f32_e32 v23, v23, v19
	s_barrier
	s_and_saveexec_b64 s[38:39], s[36:37]
	s_cbranch_execz .LBB0_1377
	v_cmp_lt_u32_e64 s[36:37], 7, v29
	v_mov_b32_e32 v28, 0
	s_and_saveexec_b64 s[40:41], s[36:37]
	s_cbranch_execz .LBB0_1364
	s_add_i32 s14, 0, 0x19800
	v_and_b32_e32 v28, 0x7ffffff8, v29
	s_mov_b32 s15, 0
	s_mov_b64 s[42:43], 0

.LBB0_1403:
	s_and_b64 vcc, exec, s[18:19]
	s_cbranch_vccz .LBB0_1227
	s_waitcnt lgkmcnt(0)
	v_readfirstlane_b32 s13, v172
	v_mov_b32_e32 v153, v3
	s_mov_b64 s[18:19], src_shared_base
	v_lshl_add_u32 v2, s13, 6, v217
	v_mov_b32_e32 v17, 0
	v_readfirstlane_b32 s13, v2
	s_ashr_i32 s90, s13, 1
	s_andn2_b32 s90, s90, 31
	v_or_b32_e32 v118, s90, v212
	v_min_i32_e32 v4, s6, v118
	v_ashrrev_i32_e32 v5, 31, v4
	v_lshlrev_b64 v[4:5], 10, v[4:5]
	v_lshl_add_u64 v[4:5], s[94:95], 0, v[4:5]
	v_lshl_add_u64 v[4:5], v[4:5], 0, v[152:153]
	global_load_dwordx4 v[94:97], v[4:5], off
	global_load_dwordx4 v[90:93], v[4:5], off offset:32
	global_load_dwordx4 v[86:89], v[4:5], off offset:64
	global_load_dwordx4 v[82:85], v[4:5], off offset:96
	v_ashrrev_i32_e32 v4, 31, v2
	v_lshrrev_b32_e32 v4, 29, v4
	v_add_u32_e32 v5, v2, v4
	v_ashrrev_i32_e32 v4, 3, v5
	v_and_b32_e32 v5, -8, v5
	v_sub_u32_e32 v6, v2, v5
	v_ashrrev_i32_e32 v5, 31, v4
	v_lshlrev_b32_e32 v120, 3, v6
	v_lshlrev_b64 v[8:9], 9, v[4:5]
	v_ashrrev_i32_e32 v121, 31, v120
	v_lshl_add_u64 v[8:9], v[8:9], 0, v[120:121]
	v_lshlrev_b64 v[8:9], 2, v[8:9]
	v_lshl_add_u64 v[10:11], s[68:69], 0, v[8:9]
	v_lshl_add_u64 v[8:9], s[76:77], 0, v[8:9]
	global_load_dwordx4 v[98:101], v[10:11], off offset:16 nt
	global_load_dwordx4 v[102:105], v[10:11], off nt
	global_load_dwordx4 v[106:109], v[8:9], off offset:16 nt
	global_load_dwordx4 v[110:113], v[8:9], off nt
	s_getreg_b32 s6, hwreg(HW_REG_HW_ID, 0, 6)
	s_and_b32 s6, s6, 63
	s_lshl_b32 s6, s6, 2
	s_add_i32 s6, s6, 0
	s_add_i32 s6, s6, 0x23e00
	v_mov_b32_e32 v8, s6
	v_mov_b32_e32 v9, s19
	flat_load_dword v5, v[8:9] sc0 sc1
	s_waitcnt vmcnt(0)
	v_mov_b32_e32 v8, 0
	s_waitcnt lgkmcnt(0)
	v_readfirstlane_b32 s6, v5
	s_nop 1
	v_lshl_add_u32 v9, s6, 6, v217
	v_lshl_add_u32 v5, v9, 3, v9
	v_cmp_gt_i32_e32 vcc, s9, v5
	v_mov_b32_e32 v200, 0
	s_and_saveexec_b64 s[20:21], vcc
	s_cbranch_execz .LBB0_1406
	v_mov_b32_e32 v7, s93
	v_mov_b32_e32 v8, s79
	v_cmp_gt_i32_e64 s[18:19], s11, v5
	s_nop 1
	v_cndmask_b32_e64 v11, v7, v8, s[18:19]
	v_mov_b32_e32 v7, s92
	v_mov_b32_e32 v8, s78
	v_cndmask_b32_e64 v10, v7, v8, s[18:19]
	v_ashrrev_i32_e32 v7, 31, v5
	v_subrev_u32_e32 v8, s11, v5
	v_cndmask_b32_e64 v13, 0, v7, s[18:19]
	v_cndmask_b32_e64 v12, v8, v5, s[18:19]
	v_lshlrev_b64 v[12:13], 5, v[12:13]
	v_lshl_add_u64 v[10:11], v[10:11], 0, v[12:13]
	global_load_dword v200, v[10:11], off

.LBB0_1422:
	s_or_b64 exec, exec, s[38:39]
	s_waitcnt vmcnt(0)
	v_add_f32_e32 v8, 0, v200
	v_add_f32_e32 v25, v8, v17
	v_add_f32_e32 v24, v25, v19
	v_add_f32_e32 v23, v24, v18
	v_add_f32_e32 v22, v23, v21
	v_add_f32_e32 v20, v22, v20
	v_add_f32_e32 v19, v20, v27
	v_add_f32_e32 v18, v19, v26
	v_add_f32_e32 v17, v18, v28
	ds_bpermute_b32 v21, v179, v17
	v_readlane_b32 s14, v244, 26
	v_readlane_b32 s15, v244, 27
	v_ashrrev_i32_e32 v27, 6, v9
	s_waitcnt lgkmcnt(0)
	v_add_f32_e32 v21, v17, v21
	v_cndmask_b32_e64 v21, v21, v17, s[0:1]
	ds_bpermute_b32 v26, v180, v21
	s_waitcnt lgkmcnt(0)
	v_add_f32_e32 v26, v21, v26
	v_cndmask_b32_e64 v21, v26, v21, s[74:75]
	ds_bpermute_b32 v26, v181, v21
	s_waitcnt lgkmcnt(0)
	v_add_f32_e32 v26, v21, v26
	v_cndmask_b32_e64 v21, v26, v21, s[14:15]
	ds_bpermute_b32 v26, v182, v21
	v_readlane_b32 s14, v244, 28
	v_readlane_b32 s15, v244, 29
	s_waitcnt lgkmcnt(0)
	v_add_f32_e32 v26, v21, v26
	v_cndmask_b32_e64 v21, v26, v21, s[14:15]
	ds_bpermute_b32 v26, v183, v21
	v_readlane_b32 s14, v244, 30
	v_readlane_b32 s15, v244, 31
	s_waitcnt lgkmcnt(0)
	v_add_f32_e32 v26, v21, v26
	v_cndmask_b32_e64 v21, v26, v21, s[14:15]
	ds_bpermute_b32 v26, v184, v21
	s_waitcnt lgkmcnt(0)
	v_add_f32_e32 v26, v21, v26
	s_mov_b64 s[36:37], exec
	v_readlane_b32 s14, v244, 34
	v_readlane_b32 s15, v244, 35
	s_and_b64 s[14:15], s[36:37], s[14:15]
	s_mov_b64 exec, s[14:15]
	v_lshl_add_u32 v28, v27, 2, 0
	v_add_u32_e32 v28, 0x19800, v28
	ds_write_b32 v28, v26
	s_or_b64 exec, exec, s[36:37]
	v_readlane_b32 s14, v244, 32
	v_readlane_b32 s15, v244, 33
	v_cmp_lt_i32_e64 s[36:37], 0, v27
	s_waitcnt lgkmcnt(0)
	v_cndmask_b32_e64 v21, v26, v21, s[14:15]
	v_sub_f32_e32 v21, v21, v17
	s_barrier
	s_and_saveexec_b64 s[38:39], s[36:37]
	s_cbranch_execz .LBB0_1442
	v_cmp_lt_u32_e64 s[36:37], 7, v27
	v_mov_b32_e32 v26, 0
	s_and_saveexec_b64 s[40:41], s[36:37]
	s_cbranch_execz .LBB0_1429
	s_add_i32 s6, 0, 0x19800
	v_and_b32_e32 v26, 0x7ffffff8, v27
	s_mov_b32 s11, 0
	s_mov_b64 s[42:43], 0
